# GLA scan: each step's leading LDS read block issued right after the barrier, ahead of the next-chunk global load block
# speedup vs baseline: 1.0055x; 1.0055x over previous
; DI void gla_scan_item(const P& p, int seq, unsigned char* smem) {
;     ...
;     auto loadr = [&](GlaRegs& R, int c) {
;         if (c >= 72) return;
;         { const int pos = tid >> 4, ch = tid & 15; R.rv = *(const u32x4*)(S + (size_t)prow(b, dir, 32 * c + pos) * NP + C_GLA_V + 128 * h + 8 * ch); }
;         { const int t2 = tid & 255, pos = t2 >> 3, ch = t2 & 7; const bf16_t* src = (tid < 256 ? QT : KO) + ((size_t)seq * PT + 32 * c + pos) * 64 + 8 * ch; R.rq = __builtin_nontemporal_load((const u32x4*)src); }
;         if (tid < 128) { const int i = tid >> 2, ch = tid & 3; R.ra = __builtin_nontemporal_load((const u32x4*)(AT + (((size_t)seq * 72 + c) * 32 + i) * 32 + 8 * ch)); }
;         if (tid >= 128 && tid < 192) R.rd = DC[((size_t)seq * 72 + c) * 64 + (tid - 128)];
;     };
;     auto storel = [&](const GlaRegs& R, int buf) {
;         unsigned char* base = smem + buf * BUFB;
;         bf16_t* sat = (bf16_t*)base; bf16_t* sqt = (bf16_t*)(base + 2560); bf16_t* sko = (bf16_t*)(base + 2560 + 4608); bf16_t* sv = (bf16_t*)(base + 2560 + 9216); float* sdc = (float*)(base + 2560 + 9216 + 8704);
;         { const int pos = tid >> 4, ch = tid & 15; *(u32x4*)(sv + pos * 136 + 8 * ch) = R.rv; }
;         { const int t2 = tid & 255, pos = t2 >> 3, ch = t2 & 7; *(u32x4*)((tid < 256 ? sqt : sko) + pos * 72 + 8 * ch) = R.rq; }
;         if (tid < 128) { const int i = tid >> 2, ch = tid & 3; *(u32x4*)(sat + i * 40 + 8 * ch) = R.ra; }
;         if (tid >= 128 && tid < 192) sdc[tid - 128] = R.rd;
;     };
;     ...
; #pragma unroll 1
;     for (int c = 0; c < 72; c += 6) {
;         storel(R0, 0); __syncthreads(); loadr(R0, c + 6); compute(c);
.LBB0_580:
	s_waitcnt vmcnt(11)
	ds_write_b128 v121, v[0:3] offset:11776
	s_waitcnt vmcnt(10)
	ds_write_b128 v122, v[8:11]
	s_and_saveexec_b64 s[36:37], s[38:39]
	ds_write_b128 v148, v[4:7]
	s_or_b64 exec, exec, s[36:37]
	s_and_saveexec_b64 s[36:37], s[40:41]
	ds_write_b32 v149, v115 offset:19968
	s_or_b64 exec, exec, s[36:37]
	s_add_i32 s24, s24, 6
	s_cmpk_gt_u32 s24, 0x41
	v_add_u32_e32 v150, s26, v114
	v_lshl_add_u64 v[112:113], v[108:109], 0, s[44:45]
	s_waitcnt lgkmcnt(0)
	s_barrier
	ds_read_b64_tr_b16 v[200:201], v123 offset:11776
	ds_read_b64_tr_b16 v[202:203], v124 offset:11776
	ds_read_b128 v[204:207], v125
	ds_read_b128 v[216:219], v127
	ds_read_b64_tr_b16 v[238:239], v144 offset:7168
	ds_read_b64_tr_b16 v[242:243], v144 offset:7200
	ds_read_b64_tr_b16 v[236:237], v143 offset:7168
	ds_read_b64_tr_b16 v[240:241], v143 offset:7200
	ds_read_b64_tr_b16 v[248:249], v143 offset:7232
	ds_read_b64_tr_b16 v[250:251], v144 offset:7232
	s_cbranch_scc1 .LBB0_590
	v_add_u32_e32 v0, 0x80, v150
	s_movk_i32 s2, 0x100
	v_cmp_gt_i32_e32 vcc, s2, v0
	v_add_u32_e32 v1, 0xffffff80, v150
	v_mov_b32_e32 v3, s22
	v_cndmask_b32_e32 v2, v174, v175, vcc
	v_add3_u32 v2, v132, v2, s27
	v_cndmask_b32_e32 v0, v1, v0, vcc
	v_mov_b32_e32 v1, s21
	v_add_u32_e32 v2, 0xfffff6e1, v2
	v_cndmask_b32_e32 v1, v1, v3, vcc
	v_cndmask_b32_e64 v0, v2, v0, s[0:1]
	v_add_u32_e32 v0, v0, v1
	s_movk_i32 s2, 0x3800
	v_add_co_u32_e32 v8, vcc, 0x6000, v112
	v_mad_i64_i32 v[0:1], s[2:3], v0, s2, v[104:105]
	s_nop 0
	v_addc_co_u32_e32 v9, vcc, 0, v113, vcc
	global_load_dwordx4 v[0:3], v[0:1], off offset:1024
	s_nop 0
	global_load_dwordx4 v[8:11], v[8:9], off nt
	s_and_saveexec_b64 s[36:37], s[38:39]
	s_cbranch_execz .LBB0_587
	v_lshl_add_u64 v[4:5], v[106:107], 0, s[44:45]
	v_add_co_u32_e32 v4, vcc, 0x1283f000, v4
	s_nop 1
	v_addc_co_u32_e32 v5, vcc, 0, v5, vcc
	global_load_dwordx4 v[4:7], v[4:5], off nt

; DI void gla_scan_item(const P& p, int seq, unsigned char* smem) {
;     ...
;     auto loadr = [&](GlaRegs& R, int c) {
;         if (c >= 72) return;
;         { const int pos = tid >> 4, ch = tid & 15; R.rv = *(const u32x4*)(S + (size_t)prow(b, dir, 32 * c + pos) * NP + C_GLA_V + 128 * h + 8 * ch); }
;         { const int t2 = tid & 255, pos = t2 >> 3, ch = t2 & 7; const bf16_t* src = (tid < 256 ? QT : KO) + ((size_t)seq * PT + 32 * c + pos) * 64 + 8 * ch; R.rq = __builtin_nontemporal_load((const u32x4*)src); }
;         if (tid < 128) { const int i = tid >> 2, ch = tid & 3; R.ra = __builtin_nontemporal_load((const u32x4*)(AT + (((size_t)seq * 72 + c) * 32 + i) * 32 + 8 * ch)); }
;     ...
;     auto compute = [&](int c) {
;         const unsigned char* base = smem + (c & 1) * BUFB;
;         const bf16_t* sat = (const bf16_t*)base; const bf16_t* sqt = (const bf16_t*)(base + 2560); const bf16_t* sko = (const bf16_t*)(base + 2560 + 4608); const bf16_t* sv = (const bf16_t*)(base + 2560 + 9216); const float* sdc = (const float*)(base + 2560 + 9216 + 8704);
;         const int dv0 = 16 * w;
;         const bf16x8 vb = tr2(sv + (8 * g + q4) * 136 + dv0 + 4 * p4, sv + (8 * g + 4 + q4) * 136 + dv0 + 4 * p4);
;         bf16x8 bs[2];
;         bs[0] = packacc(st[0], st[1]); bs[1] = packacc(st[2], st[3]);
; #pragma unroll
;         for (int mt = 0; mt < 2; ++mt) {
;             f32x4 acc = (f32x4){0.f, 0.f, 0.f, 0.f};
;             acc = mfma16(vb, ld8(sat + (16 * mt + l15) * 40 + 8 * g), acc);
; #pragma unroll
;             for (int ks = 0; ks < 2; ++ks) {
;                 const bf16_t* r0 = sqt + (16 * mt + l15) * 72 + 32 * ks + 4 * g;
;                 acc = mfma16(bs[ks], ld4x2(r0, r0 + 16), acc);
;             }
;             bf16_t* ob = OG + (size_t)prow(b, dir, 32 * c) * 512 + 128 * h;
;             u32x2 ov; ov.x = pk2(acc[0], acc[1]); ov.y = pk2(acc[2], acc[3]);
;             *(u32x2*)(ob + sgn * ((16 * mt + l15) * 512) + dv0 + 4 * g) = ov;
;         }
; #pragma unroll
;         for (int dt = 0; dt < 4; ++dt) {
;             const bf16x8 ak = tr2(sko + (8 * g + q4) * 72 + 16 * dt + 4 * p4, sko + (8 * g + 4 + q4) * 72 + 16 * dt + 4 * p4);
; #pragma unroll
;             for (int r = 0; r < 4; ++r) st[dt][r] *= sdc[16 * dt + 4 * g + r];
;             st[dt] = mfma16(ak, vb, st[dt]);
;         }
;     };
.LBB0_590:
	v_cvt_pk_bf16_f32 v96, v84, v85
	v_cvt_pk_bf16_f32 v99, v78, v79
	v_add_u32_e32 v152, 0x800, v126
	ds_read2_b64 v[208:211], v152 offset0:64 offset1:68
	ds_read2_b64 v[212:215], v152 offset0:72 offset1:76
	v_cvt_pk_bf16_f32 v98, v76, v77
	v_cvt_pk_bf16_f32 v97, v86, v87
	s_sub_i32 s4, s26, 64
	s_add_i32 s5, s26, 0xfffffec0
	s_add_i32 s6, s27, 0xa0
	s_add_i32 s7, s27, 0xfffff8a0
	s_waitcnt lgkmcnt(9)
	v_mfma_f32_16x16x32_bf16 v[92:95], v[200:203], v[204:207], 0
	s_and_b64 s[2:3], s[0:1], exec
	s_cselect_b32 s2, s4, s7
	s_add_i32 s4, s2, s22
	s_and_b64 s[2:3], s[0:1], exec
	s_waitcnt lgkmcnt(1)
	v_mfma_f32_16x16x32_bf16 v[92:95], v[96:99], v[208:211], v[92:95]
	ds_read_b64_tr_b16 v[208:209], v143 offset:7264
	ds_read_b64_tr_b16 v[210:211], v144 offset:7264
	v_cvt_pk_bf16_f32 v156, v72, v73
	v_cvt_pk_bf16_f32 v155, v82, v83
	v_cvt_pk_bf16_f32 v154, v80, v81
	v_cvt_pk_bf16_f32 v157, v74, v75
	s_cselect_b32 s2, s5, s6
	s_add_i32 s5, s2, s21
	s_cmp_lt_u32 s24, 8
	s_cselect_b64 s[36:37], -1, 0
	s_waitcnt lgkmcnt(2)
	v_mfma_f32_16x16x32_bf16 v[92:95], v[154:157], v[212:215], v[92:95]
	s_and_b64 s[2:3], s[36:37], exec
	s_cselect_b32 s2, s4, s5
	s_ashr_i32 s3, s2, 31
	s_lshl_b64 s[42:43], s[2:3], 10
	v_add_u32_e32 v151, 0x800, v142
	ds_read2_b64 v[224:227], v151 offset0:64 offset1:68
	ds_read2_b64 v[228:231], v151 offset0:72 offset1:76
	s_nop 2
	v_cvt_pk_bf16_f32 v92, v92, v93
	v_cvt_pk_bf16_f32 v93, v94, v95
	v_lshl_add_u64 v[94:95], v[100:101], 0, s[42:43]
	global_store_dwordx2 v[94:95], v[92:93], off
	v_mfma_f32_16x16x32_bf16 v[92:95], v[200:203], v[216:219], 0
	v_add_u32_e32 v153, 0x5000, v145
	ds_read2_b32 v[232:233], v153 offset1:1
	s_waitcnt lgkmcnt(2)
	v_mfma_f32_16x16x32_bf16 v[92:95], v[96:99], v[224:227], v[92:95]
	v_add_u32_e32 v158, 0x5040, v145
	ds_read2_b32 v[244:245], v158 offset1:1
	v_add_u32_e32 v161, 0x50c0, v145
	ds_read2_b32 v[212:213], v161 offset1:1
	s_waitcnt lgkmcnt(3)
	v_mfma_f32_16x16x32_bf16 v[92:95], v[154:157], v[228:231], v[92:95]
	v_add_u32_e32 v156, 0x5008, v145
	ds_read2_b32 v[234:235], v156 offset1:1
	v_add_u32_e32 v157, 0x5048, v145
	ds_read2_b32 v[246:247], v157 offset1:1
	v_add_u32_e32 v154, 0x5080, v145
	ds_read2_b32 v[204:205], v154 offset1:1
	s_nop 4
	v_cvt_pk_bf16_f32 v92, v92, v93
	v_cvt_pk_bf16_f32 v93, v94, v95
	v_lshl_add_u64 v[94:95], v[102:103], 0, s[42:43]
	global_store_dwordx2 v[94:95], v[92:93], off
	v_add_u32_e32 v155, 0x5088, v145
	ds_read2_b32 v[206:207], v155 offset1:1
	v_add_u32_e32 v160, 0x50c8, v145
	ds_read2_b32 v[214:215], v160 offset1:1
	s_waitcnt lgkmcnt(7)
	v_pk_mul_f32 v[84:85], v[84:85], v[232:233]
	s_waitcnt lgkmcnt(4)
	v_pk_mul_f32 v[86:87], v[86:87], v[234:235]
	s_nop 1
	v_mfma_f32_16x16x32_bf16 v[84:87], v[236:239], v[200:203], v[84:87]
	v_pk_mul_f32 v[76:77], v[76:77], v[244:245]
	s_waitcnt lgkmcnt(3)
	v_pk_mul_f32 v[78:79], v[78:79], v[246:247]
	s_nop 1
	v_mfma_f32_16x16x32_bf16 v[76:79], v[240:243], v[200:203], v[76:79]
	s_waitcnt lgkmcnt(2)
	v_pk_mul_f32 v[80:81], v[80:81], v[204:205]
	s_waitcnt lgkmcnt(1)
	v_pk_mul_f32 v[82:83], v[82:83], v[206:207]
	s_nop 1
	v_mfma_f32_16x16x32_bf16 v[80:83], v[248:251], v[200:203], v[80:83]
	s_waitcnt vmcnt(11)
	ds_write_b128 v121, v[12:15] offset:32512
	s_waitcnt vmcnt(10)
	ds_write_b128 v122, v[20:23] offset:20736
	v_pk_mul_f32 v[72:73], v[72:73], v[212:213]
	s_waitcnt lgkmcnt(2)
	v_pk_mul_f32 v[74:75], v[74:75], v[214:215]
	s_nop 1
	v_mfma_f32_16x16x32_bf16 v[72:75], v[208:211], v[200:203], v[72:75]
	s_and_saveexec_b64 s[42:43], s[38:39]
	ds_write_b128 v148, v[16:19] offset:20736
	s_or_b64 exec, exec, s[42:43]
	s_and_saveexec_b64 s[42:43], s[40:41]
	ds_write_b32 v149, v116 offset:40704
	s_or_b64 exec, exec, s[42:43]
	s_cmp_gt_u32 s24, 64
	s_waitcnt lgkmcnt(0)
	s_barrier
	ds_read_b64_tr_b16 v[200:201], v123 offset:32512
	ds_read_b64_tr_b16 v[202:203], v124 offset:32512
	ds_read_b128 v[204:207], v125 offset:20736
	ds_read_b128 v[216:219], v127 offset:20736
	ds_read_b64_tr_b16 v[238:239], v147 offset:27904
	ds_read_b64_tr_b16 v[242:243], v147 offset:27936
	ds_read_b64_tr_b16 v[236:237], v146 offset:27904
	ds_read_b64_tr_b16 v[240:241], v146 offset:27936
	ds_read_b64_tr_b16 v[248:249], v146 offset:27968
	ds_read_b64_tr_b16 v[250:251], v147 offset:27968
	s_cbranch_scc1 .LBB0_600
	v_add_u32_e32 v12, 0xa0, v150
	s_movk_i32 s2, 0x100
	v_cmp_gt_i32_e32 vcc, s2, v12
	v_add_u32_e32 v13, 0xffffffa0, v150
	v_mov_b32_e32 v15, s22
	v_cndmask_b32_e32 v14, v174, v175, vcc
	v_add3_u32 v14, v132, v14, s27
	v_cndmask_b32_e32 v12, v13, v12, vcc
	v_mov_b32_e32 v13, s21
	v_add_u32_e32 v14, 0xfffff6c1, v14
	v_cndmask_b32_e32 v13, v13, v15, vcc
	v_cndmask_b32_e64 v12, v14, v12, s[0:1]
	v_add_u32_e32 v12, v12, v13
	s_movk_i32 s2, 0x3800
	v_add_co_u32_e32 v20, vcc, 0x7000, v112
	v_mad_i64_i32 v[12:13], s[2:3], v12, s2, v[104:105]
	s_nop 0
	v_addc_co_u32_e32 v21, vcc, 0, v113, vcc
	global_load_dwordx4 v[12:15], v[12:13], off offset:1024
	s_nop 0
	global_load_dwordx4 v[20:23], v[20:21], off nt
	s_and_saveexec_b64 s[42:43], s[38:39]
	s_cbranch_execz .LBB0_597
	v_lshl_add_u64 v[16:17], v[106:107], 0, s[44:45]
	v_add_co_u32_e32 v16, vcc, 0x1283f000, v16
	s_nop 1
	v_addc_co_u32_e32 v17, vcc, 0, v17, vcc
	global_load_dwordx4 v[16:19], v[16:17], off offset:2048 nt

; DI void gla_scan_item(const P& p, int seq, unsigned char* smem) {
;     ...
;     auto loadr = [&](GlaRegs& R, int c) {
;         if (c >= 72) return;
;         { const int pos = tid >> 4, ch = tid & 15; R.rv = *(const u32x4*)(S + (size_t)prow(b, dir, 32 * c + pos) * NP + C_GLA_V + 128 * h + 8 * ch); }
;         { const int t2 = tid & 255, pos = t2 >> 3, ch = t2 & 7; const bf16_t* src = (tid < 256 ? QT : KO) + ((size_t)seq * PT + 32 * c + pos) * 64 + 8 * ch; R.rq = __builtin_nontemporal_load((const u32x4*)src); }
;         if (tid < 128) { const int i = tid >> 2, ch = tid & 3; R.ra = __builtin_nontemporal_load((const u32x4*)(AT + (((size_t)seq * 72 + c) * 32 + i) * 32 + 8 * ch)); }
;     ...
;     auto compute = [&](int c) {
;         const unsigned char* base = smem + (c & 1) * BUFB;
;         const bf16_t* sat = (const bf16_t*)base; const bf16_t* sqt = (const bf16_t*)(base + 2560); const bf16_t* sko = (const bf16_t*)(base + 2560 + 4608); const bf16_t* sv = (const bf16_t*)(base + 2560 + 9216); const float* sdc = (const float*)(base + 2560 + 9216 + 8704);
;         const int dv0 = 16 * w;
;         const bf16x8 vb = tr2(sv + (8 * g + q4) * 136 + dv0 + 4 * p4, sv + (8 * g + 4 + q4) * 136 + dv0 + 4 * p4);
;         bf16x8 bs[2];
;         bs[0] = packacc(st[0], st[1]); bs[1] = packacc(st[2], st[3]);
; #pragma unroll
;         for (int mt = 0; mt < 2; ++mt) {
;             f32x4 acc = (f32x4){0.f, 0.f, 0.f, 0.f};
;             acc = mfma16(vb, ld8(sat + (16 * mt + l15) * 40 + 8 * g), acc);
; #pragma unroll
;             for (int ks = 0; ks < 2; ++ks) {
;                 const bf16_t* r0 = sqt + (16 * mt + l15) * 72 + 32 * ks + 4 * g;
;                 acc = mfma16(bs[ks], ld4x2(r0, r0 + 16), acc);
;             }
;             bf16_t* ob = OG + (size_t)prow(b, dir, 32 * c) * 512 + 128 * h;
;             u32x2 ov; ov.x = pk2(acc[0], acc[1]); ov.y = pk2(acc[2], acc[3]);
;             *(u32x2*)(ob + sgn * ((16 * mt + l15) * 512) + dv0 + 4 * g) = ov;
;         }
; #pragma unroll
;         for (int dt = 0; dt < 4; ++dt) {
;             const bf16x8 ak = tr2(sko + (8 * g + q4) * 72 + 16 * dt + 4 * p4, sko + (8 * g + 4 + q4) * 72 + 16 * dt + 4 * p4);
; #pragma unroll
;             for (int r = 0; r < 4; ++r) st[dt][r] *= sdc[16 * dt + 4 * g + r];
;             st[dt] = mfma16(ak, vb, st[dt]);
;         }
;     };
.LBB0_600:
	v_cvt_pk_bf16_f32 v96, v84, v85
	v_cvt_pk_bf16_f32 v99, v78, v79
	v_add_u32_e32 v159, 0x5800, v126
	ds_read2_b64 v[208:211], v159 offset0:96 offset1:100
	ds_read2_b64 v[212:215], v159 offset0:104 offset1:108
	v_cvt_pk_bf16_f32 v98, v76, v77
	v_cvt_pk_bf16_f32 v97, v86, v87
	s_waitcnt lgkmcnt(9)
	v_mfma_f32_16x16x32_bf16 v[88:91], v[200:203], v[204:207], 0
	s_sub_i32 s4, s26, 32
	s_add_i32 s5, s26, 0xfffffee0
	s_add_i32 s6, s27, 0x80
	s_add_i32 s7, s27, 0xfffff880
	s_and_b64 s[2:3], s[0:1], exec
	s_waitcnt lgkmcnt(1)
	v_mfma_f32_16x16x32_bf16 v[162:165], v[96:99], v[208:211], v[88:91]
	ds_read_b64_tr_b16 v[208:209], v146 offset:28000
	ds_read_b64_tr_b16 v[210:211], v147 offset:28000
	s_cselect_b32 s2, s4, s7
	s_add_i32 s4, s2, s22
	s_and_b64 s[2:3], s[0:1], exec
	v_cvt_pk_bf16_f32 v90, v72, v73
	v_cvt_pk_bf16_f32 v89, v82, v83
	v_cvt_pk_bf16_f32 v88, v80, v81
	v_cvt_pk_bf16_f32 v91, v74, v75
	s_cselect_b32 s2, s5, s6
	s_add_i32 s5, s2, s21
	s_waitcnt lgkmcnt(2)
	v_mfma_f32_16x16x32_bf16 v[162:165], v[88:91], v[212:215], v[162:165]
	s_and_b64 s[2:3], s[36:37], exec
	s_cselect_b32 s2, s4, s5
	s_ashr_i32 s3, s2, 31
	s_lshl_b64 s[36:37], s[2:3], 10
	s_nop 3
	v_cvt_pk_bf16_f32 v134, v162, v163
	v_cvt_pk_bf16_f32 v135, v164, v165
	v_lshl_add_u64 v[162:163], v[100:101], 0, s[36:37]
	global_store_dwordx2 v[162:163], v[134:135], off
	v_mfma_f32_16x16x32_bf16 v[184:187], v[200:203], v[216:219], 0
	v_add_u32_e32 v162, 0x5800, v142
	ds_read2_b64 v[224:227], v162 offset0:96 offset1:100
	ds_read2_b64 v[228:231], v162 offset0:104 offset1:108
	v_add_u32_e32 v163, 0xa100, v145
	ds_read2_b32 v[232:233], v163 offset1:1
	s_waitcnt lgkmcnt(2)
	v_mfma_f32_16x16x32_bf16 v[96:99], v[96:99], v[224:227], v[184:187]
	s_nop 2
	v_add_u32_e32 v183, 0xa108, v145
	ds_read2_b32 v[234:235], v183 offset1:1
	v_add_u32_e32 v164, 0xa180, v145
	ds_read2_b32 v[204:205], v164 offset1:1
	s_waitcnt lgkmcnt(3)
	v_mfma_f32_16x16x32_bf16 v[88:91], v[88:91], v[228:231], v[96:99]
	v_add_u32_e32 v185, 0xa140, v145
	ds_read2_b32 v[244:245], v185 offset1:1
	v_add_u32_e32 v184, 0xa148, v145
	ds_read2_b32 v[246:247], v184 offset1:1
	v_add_u32_e32 v165, 0xa188, v145
	ds_read2_b32 v[206:207], v165 offset1:1
	s_nop 4
	v_cvt_pk_bf16_f32 v88, v88, v89
	v_cvt_pk_bf16_f32 v89, v90, v91
	v_lshl_add_u64 v[90:91], v[102:103], 0, s[36:37]
	global_store_dwordx2 v[90:91], v[88:89], off
	v_add_u32_e32 v187, 0xa1c0, v145
	ds_read2_b32 v[212:213], v187 offset1:1
	v_add_u32_e32 v186, 0xa1c8, v145
	ds_read2_b32 v[214:215], v186 offset1:1
	s_waitcnt lgkmcnt(7)
	v_pk_mul_f32 v[84:85], v[84:85], v[232:233]
	s_waitcnt lgkmcnt(6)
	v_pk_mul_f32 v[86:87], v[86:87], v[234:235]
	s_nop 1
	v_mfma_f32_16x16x32_bf16 v[88:91], v[236:239], v[200:203], v[84:87]
	s_nop 2
	s_waitcnt lgkmcnt(4)
	v_pk_mul_f32 v[76:77], v[76:77], v[244:245]
	s_waitcnt lgkmcnt(3)
	v_pk_mul_f32 v[78:79], v[78:79], v[246:247]
	s_nop 1
	v_mfma_f32_16x16x32_bf16 v[84:87], v[240:243], v[200:203], v[76:79]
	s_nop 2
	v_pk_mul_f32 v[80:81], v[80:81], v[204:205]
	s_waitcnt lgkmcnt(2)
	v_pk_mul_f32 v[82:83], v[82:83], v[206:207]
	s_nop 1
	v_mfma_f32_16x16x32_bf16 v[76:79], v[248:251], v[200:203], v[80:83]
	s_nop 2
	s_waitcnt vmcnt(11)
	ds_write_b128 v121, v[24:27] offset:11776
	s_waitcnt vmcnt(10)
	ds_write_b128 v122, v[32:35]
	s_waitcnt lgkmcnt(3)
	v_pk_mul_f32 v[72:73], v[72:73], v[212:213]
	s_waitcnt lgkmcnt(2)
	v_pk_mul_f32 v[74:75], v[74:75], v[214:215]
	s_nop 1
	v_mfma_f32_16x16x32_bf16 v[80:83], v[208:211], v[200:203], v[72:75]
	s_and_saveexec_b64 s[36:37], s[38:39]
	ds_write_b128 v148, v[28:31]
	s_or_b64 exec, exec, s[36:37]
	s_and_saveexec_b64 s[36:37], s[40:41]
	ds_write_b32 v149, v117 offset:19968
	s_or_b64 exec, exec, s[36:37]
	s_cmp_gt_u32 s24, 63
	s_waitcnt lgkmcnt(0)
	s_barrier
	ds_read_b64_tr_b16 v[200:201], v123 offset:11776
	ds_read_b64_tr_b16 v[202:203], v124 offset:11776
	ds_read_b128 v[204:207], v125
	ds_read2_b64 v[208:211], v152 offset0:64 offset1:68
	ds_read2_b64 v[212:215], v152 offset0:72 offset1:76
	ds_read2_b64 v[216:219], v151 offset0:64 offset1:68
	ds_read_b128 v[224:227], v127
	ds_read2_b64 v[228:231], v151 offset0:72 offset1:76
	ds_read2_b32 v[232:233], v153 offset1:1
	ds_read2_b32 v[234:235], v156 offset1:1
	ds_read_b64_tr_b16 v[238:239], v144 offset:7168
	ds_read_b64_tr_b16 v[242:243], v144 offset:7200
	s_cbranch_scc1 .LBB0_610
	v_add_u32_e32 v24, 0xc0, v150
	s_movk_i32 s2, 0x100
	v_cmp_gt_i32_e32 vcc, s2, v24
	v_subrev_u32_e32 v25, 64, v150
	v_mov_b32_e32 v27, s22
	v_cndmask_b32_e32 v26, v174, v175, vcc
	v_add3_u32 v26, v132, v26, s27
	v_cndmask_b32_e32 v24, v25, v24, vcc
	v_mov_b32_e32 v25, s21
	v_add_u32_e32 v26, 0xfffff6a1, v26
	v_cndmask_b32_e32 v25, v25, v27, vcc
	v_cndmask_b32_e64 v24, v26, v24, s[0:1]
	v_add_u32_e32 v24, v24, v25
	s_movk_i32 s2, 0x3800
	v_add_co_u32_e32 v32, vcc, 0x8000, v112
	v_mad_i64_i32 v[24:25], s[2:3], v24, s2, v[104:105]
	s_nop 0
	v_addc_co_u32_e32 v33, vcc, 0, v113, vcc
	global_load_dwordx4 v[24:27], v[24:25], off offset:1024
	s_nop 0
	global_load_dwordx4 v[32:35], v[32:33], off nt
	s_and_saveexec_b64 s[36:37], s[38:39]
	s_cbranch_execz .LBB0_607
	v_lshl_add_u64 v[28:29], v[106:107], 0, s[44:45]
	v_add_co_u32_e32 v28, vcc, 0x12840000, v28
	s_nop 1
	v_addc_co_u32_e32 v29, vcc, 0, v29, vcc
	global_load_dwordx4 v[28:31], v[28:29], off nt

; DI void gla_scan_item(const P& p, int seq, unsigned char* smem) {
;     ...
;     auto loadr = [&](GlaRegs& R, int c) {
;         if (c >= 72) return;
;         { const int pos = tid >> 4, ch = tid & 15; R.rv = *(const u32x4*)(S + (size_t)prow(b, dir, 32 * c + pos) * NP + C_GLA_V + 128 * h + 8 * ch); }
;         { const int t2 = tid & 255, pos = t2 >> 3, ch = t2 & 7; const bf16_t* src = (tid < 256 ? QT : KO) + ((size_t)seq * PT + 32 * c + pos) * 64 + 8 * ch; R.rq = __builtin_nontemporal_load((const u32x4*)src); }
;         if (tid < 128) { const int i = tid >> 2, ch = tid & 3; R.ra = __builtin_nontemporal_load((const u32x4*)(AT + (((size_t)seq * 72 + c) * 32 + i) * 32 + 8 * ch)); }
;     ...
;     auto compute = [&](int c) {
;         const unsigned char* base = smem + (c & 1) * BUFB;
;         const bf16_t* sat = (const bf16_t*)base; const bf16_t* sqt = (const bf16_t*)(base + 2560); const bf16_t* sko = (const bf16_t*)(base + 2560 + 4608); const bf16_t* sv = (const bf16_t*)(base + 2560 + 9216); const float* sdc = (const float*)(base + 2560 + 9216 + 8704);
;         const int dv0 = 16 * w;
;         const bf16x8 vb = tr2(sv + (8 * g + q4) * 136 + dv0 + 4 * p4, sv + (8 * g + 4 + q4) * 136 + dv0 + 4 * p4);
;         bf16x8 bs[2];
;         bs[0] = packacc(st[0], st[1]); bs[1] = packacc(st[2], st[3]);
; #pragma unroll
;         for (int mt = 0; mt < 2; ++mt) {
;             f32x4 acc = (f32x4){0.f, 0.f, 0.f, 0.f};
;             acc = mfma16(vb, ld8(sat + (16 * mt + l15) * 40 + 8 * g), acc);
; #pragma unroll
;             for (int ks = 0; ks < 2; ++ks) {
;                 const bf16_t* r0 = sqt + (16 * mt + l15) * 72 + 32 * ks + 4 * g;
;                 acc = mfma16(bs[ks], ld4x2(r0, r0 + 16), acc);
;             }
;             bf16_t* ob = OG + (size_t)prow(b, dir, 32 * c) * 512 + 128 * h;
;             u32x2 ov; ov.x = pk2(acc[0], acc[1]); ov.y = pk2(acc[2], acc[3]);
;             *(u32x2*)(ob + sgn * ((16 * mt + l15) * 512) + dv0 + 4 * g) = ov;
;         }
; #pragma unroll
;         for (int dt = 0; dt < 4; ++dt) {
;             const bf16x8 ak = tr2(sko + (8 * g + q4) * 72 + 16 * dt + 4 * p4, sko + (8 * g + 4 + q4) * 72 + 16 * dt + 4 * p4);
; #pragma unroll
;             for (int r = 0; r < 4; ++r) st[dt][r] *= sdc[16 * dt + 4 * g + r];
;             st[dt] = mfma16(ak, vb, st[dt]);
;         }
;     };
.LBB0_610:
	v_cvt_pk_bf16_f32 v98, v84, v85
	v_cvt_pk_bf16_f32 v97, v90, v91
	v_cvt_pk_bf16_f32 v96, v88, v89
	v_cvt_pk_bf16_f32 v99, v86, v87
	s_waitcnt lgkmcnt(9)
	v_mfma_f32_16x16x32_bf16 v[72:75], v[200:203], v[204:207], 0
	ds_read_b64_tr_b16 v[236:237], v143 offset:7168
	ds_read_b64_tr_b16 v[240:241], v143 offset:7200
	ds_read2_b32 v[244:245], v158 offset1:1
	s_add_i32 s4, s26, 0xffffff00
	s_add_i32 s5, s27, 0x60
	s_add_i32 s6, s27, 0xfffff860
	s_and_b64 s[2:3], s[0:1], exec
	s_cselect_b32 s2, s26, s6
	s_waitcnt lgkmcnt(11)
	v_mfma_f32_16x16x32_bf16 v[72:75], v[96:99], v[208:211], v[72:75]
	ds_read2_b32 v[246:247], v157 offset1:1
	v_cvt_pk_bf16_f32 v190, v80, v81
	v_cvt_pk_bf16_f32 v189, v78, v79
	v_cvt_pk_bf16_f32 v188, v76, v77
	v_cvt_pk_bf16_f32 v191, v82, v83
	s_add_i32 s6, s2, s22
	s_and_b64 s[2:3], s[0:1], exec
	s_cselect_b32 s2, s4, s5
	s_add_i32 s2, s2, s21
	s_cmp_lt_u32 s24, 6
	s_waitcnt lgkmcnt(11)
	v_mfma_f32_16x16x32_bf16 v[72:75], v[188:191], v[212:215], v[72:75]
	ds_read_b64_tr_b16 v[248:249], v143 offset:7232
	s_cselect_b32 s2, s6, s2
	s_ashr_i32 s3, s2, 31
	s_lshl_b64 s[36:37], s[2:3], 10
	s_nop 3
	v_cvt_pk_bf16_f32 v72, v72, v73
	v_cvt_pk_bf16_f32 v73, v74, v75
	v_lshl_add_u64 v[74:75], v[100:101], 0, s[36:37]
	global_store_dwordx2 v[74:75], v[72:73], off
	s_waitcnt lgkmcnt(10)
	v_mfma_f32_16x16x32_bf16 v[72:75], v[200:203], v[224:227], 0
	ds_read_b64_tr_b16 v[250:251], v144 offset:7232
	ds_read2_b32 v[204:205], v154 offset1:1
	v_mfma_f32_16x16x32_bf16 v[72:75], v[96:99], v[216:219], v[72:75]
	s_waitcnt lgkmcnt(11)
	v_mfma_f32_16x16x32_bf16 v[72:75], v[188:191], v[228:231], v[72:75]
	ds_read2_b32 v[206:207], v155 offset1:1
	s_nop 7
	v_cvt_pk_bf16_f32 v72, v72, v73
	v_cvt_pk_bf16_f32 v73, v74, v75
	v_lshl_add_u64 v[74:75], v[102:103], 0, s[36:37]
	global_store_dwordx2 v[74:75], v[72:73], off
	s_waitcnt lgkmcnt(11)
	v_pk_mul_f32 v[72:73], v[88:89], v[232:233]
	ds_read_b64_tr_b16 v[208:209], v143 offset:7264
	s_waitcnt lgkmcnt(11)
	v_pk_mul_f32 v[74:75], v[90:91], v[234:235]
	ds_read_b64_tr_b16 v[210:211], v144 offset:7264
	s_waitcnt lgkmcnt(9)
	v_mfma_f32_16x16x32_bf16 v[88:91], v[236:239], v[200:203], v[72:75]
	ds_read2_b32 v[212:213], v161 offset1:1
	ds_read2_b32 v[214:215], v160 offset1:1
	s_nop 2
	s_waitcnt lgkmcnt(9)
	v_pk_mul_f32 v[72:73], v[84:85], v[244:245]
	s_waitcnt lgkmcnt(8)
	v_pk_mul_f32 v[74:75], v[86:87], v[246:247]
	s_nop 1
	v_mfma_f32_16x16x32_bf16 v[72:75], v[240:243], v[200:203], v[72:75]
	s_waitcnt lgkmcnt(5)
	v_pk_mul_f32 v[76:77], v[76:77], v[204:205]
	s_waitcnt lgkmcnt(4)
	v_pk_mul_f32 v[78:79], v[78:79], v[206:207]
	s_nop 1
	v_mfma_f32_16x16x32_bf16 v[76:79], v[248:251], v[200:203], v[76:79]
	s_waitcnt vmcnt(11)
	ds_write_b128 v121, v[36:39] offset:32512
	s_waitcnt vmcnt(10)
	ds_write_b128 v122, v[44:47] offset:20736
	s_waitcnt lgkmcnt(3)
	v_pk_mul_f32 v[80:81], v[80:81], v[212:213]
	s_waitcnt lgkmcnt(2)
	v_pk_mul_f32 v[82:83], v[82:83], v[214:215]
	s_nop 1
	v_mfma_f32_16x16x32_bf16 v[80:83], v[208:211], v[200:203], v[80:83]
	s_and_saveexec_b64 s[36:37], s[38:39]
	ds_write_b128 v148, v[40:43] offset:20736
	s_or_b64 exec, exec, s[36:37]
	s_and_saveexec_b64 s[36:37], s[40:41]
	ds_write_b32 v149, v118 offset:40704
	s_or_b64 exec, exec, s[36:37]
	s_cmp_gt_u32 s24, 62
	s_waitcnt lgkmcnt(0)
	s_barrier
	ds_read_b64_tr_b16 v[200:201], v123 offset:32512
	ds_read_b64_tr_b16 v[202:203], v124 offset:32512
	ds_read_b128 v[204:207], v125 offset:20736
	ds_read2_b64 v[208:211], v159 offset0:96 offset1:100
	ds_read2_b64 v[212:215], v159 offset0:104 offset1:108
	ds_read2_b64 v[216:219], v162 offset0:96 offset1:100
	ds_read_b128 v[224:227], v127 offset:20736
	ds_read2_b64 v[228:231], v162 offset0:104 offset1:108
	ds_read2_b32 v[232:233], v163 offset1:1
	ds_read2_b32 v[234:235], v183 offset1:1
	ds_read_b64_tr_b16 v[238:239], v147 offset:27904
	ds_read_b64_tr_b16 v[242:243], v147 offset:27936
	s_cbranch_scc1 .LBB0_620
	v_add_u32_e32 v36, 0xe0, v150
	s_movk_i32 s2, 0x100
	v_cmp_gt_i32_e32 vcc, s2, v36
	v_subrev_u32_e32 v37, 32, v150
	v_mov_b32_e32 v39, s22
	v_cndmask_b32_e32 v38, v174, v175, vcc
	v_add3_u32 v38, v132, v38, s27
	v_cndmask_b32_e32 v36, v37, v36, vcc
	v_mov_b32_e32 v37, s21
	v_add_u32_e32 v38, 0xfffff681, v38
	v_cndmask_b32_e32 v37, v37, v39, vcc
	v_cndmask_b32_e64 v36, v38, v36, s[0:1]
	v_add_u32_e32 v36, v36, v37
	s_movk_i32 s2, 0x3800
	v_add_co_u32_e32 v44, vcc, 0x9000, v112
	v_mad_i64_i32 v[36:37], s[2:3], v36, s2, v[104:105]
	s_nop 0
	v_addc_co_u32_e32 v45, vcc, 0, v113, vcc
	global_load_dwordx4 v[36:39], v[36:37], off offset:1024
	s_nop 0
	global_load_dwordx4 v[44:47], v[44:45], off nt
	s_and_saveexec_b64 s[36:37], s[38:39]
	s_cbranch_execz .LBB0_617
	v_lshl_add_u64 v[40:41], v[106:107], 0, s[44:45]
	v_add_co_u32_e32 v40, vcc, 0x12840000, v40
	s_nop 1
	v_addc_co_u32_e32 v41, vcc, 0, v41, vcc
	global_load_dwordx4 v[40:43], v[40:41], off offset:2048 nt

; DI void gla_scan_item(const P& p, int seq, unsigned char* smem) {
;     ...
;     auto loadr = [&](GlaRegs& R, int c) {
;         if (c >= 72) return;
;         { const int pos = tid >> 4, ch = tid & 15; R.rv = *(const u32x4*)(S + (size_t)prow(b, dir, 32 * c + pos) * NP + C_GLA_V + 128 * h + 8 * ch); }
;         { const int t2 = tid & 255, pos = t2 >> 3, ch = t2 & 7; const bf16_t* src = (tid < 256 ? QT : KO) + ((size_t)seq * PT + 32 * c + pos) * 64 + 8 * ch; R.rq = __builtin_nontemporal_load((const u32x4*)src); }
;         if (tid < 128) { const int i = tid >> 2, ch = tid & 3; R.ra = __builtin_nontemporal_load((const u32x4*)(AT + (((size_t)seq * 72 + c) * 32 + i) * 32 + 8 * ch)); }
;     ...
;     auto compute = [&](int c) {
;         const unsigned char* base = smem + (c & 1) * BUFB;
;         const bf16_t* sat = (const bf16_t*)base; const bf16_t* sqt = (const bf16_t*)(base + 2560); const bf16_t* sko = (const bf16_t*)(base + 2560 + 4608); const bf16_t* sv = (const bf16_t*)(base + 2560 + 9216); const float* sdc = (const float*)(base + 2560 + 9216 + 8704);
;         const int dv0 = 16 * w;
;         const bf16x8 vb = tr2(sv + (8 * g + q4) * 136 + dv0 + 4 * p4, sv + (8 * g + 4 + q4) * 136 + dv0 + 4 * p4);
;         bf16x8 bs[2];
;         bs[0] = packacc(st[0], st[1]); bs[1] = packacc(st[2], st[3]);
; #pragma unroll
;         for (int mt = 0; mt < 2; ++mt) {
;             f32x4 acc = (f32x4){0.f, 0.f, 0.f, 0.f};
;             acc = mfma16(vb, ld8(sat + (16 * mt + l15) * 40 + 8 * g), acc);
; #pragma unroll
;             for (int ks = 0; ks < 2; ++ks) {
;                 const bf16_t* r0 = sqt + (16 * mt + l15) * 72 + 32 * ks + 4 * g;
;                 acc = mfma16(bs[ks], ld4x2(r0, r0 + 16), acc);
;             }
;             bf16_t* ob = OG + (size_t)prow(b, dir, 32 * c) * 512 + 128 * h;
;             u32x2 ov; ov.x = pk2(acc[0], acc[1]); ov.y = pk2(acc[2], acc[3]);
;             *(u32x2*)(ob + sgn * ((16 * mt + l15) * 512) + dv0 + 4 * g) = ov;
;         }
; #pragma unroll
;         for (int dt = 0; dt < 4; ++dt) {
;             const bf16x8 ak = tr2(sko + (8 * g + q4) * 72 + 16 * dt + 4 * p4, sko + (8 * g + 4 + q4) * 72 + 16 * dt + 4 * p4);
; #pragma unroll
;             for (int r = 0; r < 4; ++r) st[dt][r] *= sdc[16 * dt + 4 * g + r];
;             st[dt] = mfma16(ak, vb, st[dt]);
;         }
;     };
.LBB0_620:
	v_cvt_pk_bf16_f32 v98, v72, v73
	v_cvt_pk_bf16_f32 v97, v90, v91
	v_cvt_pk_bf16_f32 v96, v88, v89
	v_cvt_pk_bf16_f32 v99, v74, v75
	s_waitcnt lgkmcnt(9)
	v_mfma_f32_16x16x32_bf16 v[92:95], v[200:203], v[204:207], 0
	ds_read_b64_tr_b16 v[236:237], v146 offset:27904
	ds_read_b64_tr_b16 v[240:241], v146 offset:27936
	ds_read2_b32 v[244:245], v185 offset1:1
	s_add_i32 s4, s26, 32
	s_add_i32 s5, s26, 0xffffff20
	s_add_i32 s6, s27, 64
	s_add_i32 s7, s27, 0xfffff840
	s_and_b64 s[2:3], s[0:1], exec
	s_cselect_b32 s2, s4, s7
	s_waitcnt lgkmcnt(11)
	v_mfma_f32_16x16x32_bf16 v[92:95], v[96:99], v[208:211], v[92:95]
	ds_read2_b32 v[246:247], v184 offset1:1
	v_cvt_pk_bf16_f32 v190, v80, v81
	v_cvt_pk_bf16_f32 v189, v78, v79
	v_cvt_pk_bf16_f32 v188, v76, v77
	v_cvt_pk_bf16_f32 v191, v82, v83
	s_add_i32 s4, s2, s22
	s_and_b64 s[2:3], s[0:1], exec
	s_cselect_b32 s2, s5, s6
	s_add_i32 s2, s2, s21
	s_cmp_lt_u32 s24, 5
	s_waitcnt lgkmcnt(11)
	v_mfma_f32_16x16x32_bf16 v[92:95], v[188:191], v[212:215], v[92:95]
	ds_read_b64_tr_b16 v[248:249], v146 offset:27968
	s_cselect_b32 s2, s4, s2
	s_ashr_i32 s3, s2, 31
	s_lshl_b64 s[36:37], s[2:3], 10
	s_nop 3
	v_cvt_pk_bf16_f32 v92, v92, v93
	v_cvt_pk_bf16_f32 v93, v94, v95
	v_lshl_add_u64 v[94:95], v[100:101], 0, s[36:37]
	global_store_dwordx2 v[94:95], v[92:93], off
	s_waitcnt lgkmcnt(10)
	v_mfma_f32_16x16x32_bf16 v[92:95], v[200:203], v[224:227], 0
	ds_read_b64_tr_b16 v[250:251], v147 offset:27968
	ds_read2_b32 v[204:205], v164 offset1:1
	v_mfma_f32_16x16x32_bf16 v[92:95], v[96:99], v[216:219], v[92:95]
	s_waitcnt lgkmcnt(11)
	v_mfma_f32_16x16x32_bf16 v[92:95], v[188:191], v[228:231], v[92:95]
	ds_read2_b32 v[206:207], v165 offset1:1
	s_nop 7
	v_cvt_pk_bf16_f32 v92, v92, v93
	v_cvt_pk_bf16_f32 v93, v94, v95
	v_lshl_add_u64 v[94:95], v[102:103], 0, s[36:37]
	global_store_dwordx2 v[94:95], v[92:93], off
	s_waitcnt lgkmcnt(11)
	v_pk_mul_f32 v[88:89], v[88:89], v[232:233]
	ds_read_b64_tr_b16 v[208:209], v146 offset:28000
	s_waitcnt lgkmcnt(11)
	v_pk_mul_f32 v[90:91], v[90:91], v[234:235]
	ds_read_b64_tr_b16 v[210:211], v147 offset:28000
	s_waitcnt lgkmcnt(9)
	v_mfma_f32_16x16x32_bf16 v[88:91], v[236:239], v[200:203], v[88:91]
	ds_read2_b32 v[212:213], v187 offset1:1
	ds_read2_b32 v[214:215], v186 offset1:1
	s_waitcnt lgkmcnt(9)
	v_pk_mul_f32 v[72:73], v[72:73], v[244:245]
	s_waitcnt lgkmcnt(8)
	v_pk_mul_f32 v[74:75], v[74:75], v[246:247]
	s_nop 1
	v_mfma_f32_16x16x32_bf16 v[72:75], v[240:243], v[200:203], v[72:75]
	s_waitcnt lgkmcnt(5)
	v_pk_mul_f32 v[76:77], v[76:77], v[204:205]
	s_waitcnt lgkmcnt(4)
	v_pk_mul_f32 v[78:79], v[78:79], v[206:207]
	s_nop 1
	v_mfma_f32_16x16x32_bf16 v[76:79], v[248:251], v[200:203], v[76:79]
	s_waitcnt vmcnt(11)
	ds_write_b128 v121, v[48:51] offset:11776
	s_waitcnt vmcnt(10)
	ds_write_b128 v122, v[56:59]
	s_waitcnt lgkmcnt(3)
	v_pk_mul_f32 v[80:81], v[80:81], v[212:213]
	s_waitcnt lgkmcnt(2)
	v_pk_mul_f32 v[82:83], v[82:83], v[214:215]
	s_nop 1
	v_mfma_f32_16x16x32_bf16 v[84:87], v[208:211], v[200:203], v[80:83]
	s_and_saveexec_b64 s[36:37], s[38:39]
	ds_write_b128 v148, v[52:55]
	s_or_b64 exec, exec, s[36:37]
	s_and_saveexec_b64 s[36:37], s[40:41]
	ds_write_b32 v149, v119 offset:19968
	s_or_b64 exec, exec, s[36:37]
	s_cmp_gt_u32 s24, 61
	s_waitcnt lgkmcnt(0)
	s_barrier
	ds_read_b64_tr_b16 v[200:201], v123 offset:11776
	ds_read_b64_tr_b16 v[202:203], v124 offset:11776
	ds_read_b128 v[204:207], v125
	ds_read2_b64 v[208:211], v152 offset0:64 offset1:68
	ds_read2_b64 v[212:215], v152 offset0:72 offset1:76
	ds_read2_b64 v[216:219], v151 offset0:64 offset1:68
	ds_read_b128 v[224:227], v127
	ds_read2_b64 v[228:231], v151 offset0:72 offset1:76
	ds_read2_b32 v[232:233], v153 offset1:1
	ds_read2_b32 v[234:235], v156 offset1:1
	ds_read_b64_tr_b16 v[238:239], v144 offset:7168
	ds_read_b64_tr_b16 v[242:243], v144 offset:7200
	s_cbranch_scc1 .LBB0_630
	v_add_u32_e32 v48, 0x100, v150
	s_movk_i32 s2, 0x100
	v_cmp_gt_i32_e32 vcc, s2, v48
	v_mov_b32_e32 v50, s21
	v_mov_b32_e32 v51, s22
	v_cndmask_b32_e32 v49, v174, v175, vcc
	v_add3_u32 v49, v132, v49, s27
	v_cndmask_b32_e32 v48, v150, v48, vcc
	v_add_u32_e32 v49, 0xfffff661, v49
	v_cndmask_b32_e32 v50, v50, v51, vcc
	v_cndmask_b32_e64 v48, v49, v48, s[0:1]
	v_add_u32_e32 v48, v48, v50
	s_movk_i32 s2, 0x3800
	v_add_co_u32_e32 v56, vcc, 0xa000, v112
	v_mad_i64_i32 v[48:49], s[2:3], v48, s2, v[104:105]
	s_nop 0
	v_addc_co_u32_e32 v57, vcc, 0, v113, vcc
	global_load_dwordx4 v[48:51], v[48:49], off offset:1024
	s_nop 0
	global_load_dwordx4 v[56:59], v[56:57], off nt
	s_and_saveexec_b64 s[36:37], s[38:39]
	s_cbranch_execz .LBB0_627
	v_lshl_add_u64 v[52:53], v[106:107], 0, s[44:45]
	v_add_co_u32_e32 v52, vcc, 0x12841000, v52
	s_nop 1
	v_addc_co_u32_e32 v53, vcc, 0, v53, vcc
	global_load_dwordx4 v[52:55], v[52:53], off nt

; DI void gla_scan_item(const P& p, int seq, unsigned char* smem) {
;     ...
;     auto loadr = [&](GlaRegs& R, int c) {
;         if (c >= 72) return;
;         { const int pos = tid >> 4, ch = tid & 15; R.rv = *(const u32x4*)(S + (size_t)prow(b, dir, 32 * c + pos) * NP + C_GLA_V + 128 * h + 8 * ch); }
;         { const int t2 = tid & 255, pos = t2 >> 3, ch = t2 & 7; const bf16_t* src = (tid < 256 ? QT : KO) + ((size_t)seq * PT + 32 * c + pos) * 64 + 8 * ch; R.rq = __builtin_nontemporal_load((const u32x4*)src); }
;         if (tid < 128) { const int i = tid >> 2, ch = tid & 3; R.ra = __builtin_nontemporal_load((const u32x4*)(AT + (((size_t)seq * 72 + c) * 32 + i) * 32 + 8 * ch)); }
;     ...
;     auto compute = [&](int c) {
;         const unsigned char* base = smem + (c & 1) * BUFB;
;         const bf16_t* sat = (const bf16_t*)base; const bf16_t* sqt = (const bf16_t*)(base + 2560); const bf16_t* sko = (const bf16_t*)(base + 2560 + 4608); const bf16_t* sv = (const bf16_t*)(base + 2560 + 9216); const float* sdc = (const float*)(base + 2560 + 9216 + 8704);
;         const int dv0 = 16 * w;
;         const bf16x8 vb = tr2(sv + (8 * g + q4) * 136 + dv0 + 4 * p4, sv + (8 * g + 4 + q4) * 136 + dv0 + 4 * p4);
;         bf16x8 bs[2];
;         bs[0] = packacc(st[0], st[1]); bs[1] = packacc(st[2], st[3]);
; #pragma unroll
;         for (int mt = 0; mt < 2; ++mt) {
;             f32x4 acc = (f32x4){0.f, 0.f, 0.f, 0.f};
;             acc = mfma16(vb, ld8(sat + (16 * mt + l15) * 40 + 8 * g), acc);
; #pragma unroll
;             for (int ks = 0; ks < 2; ++ks) {
;                 const bf16_t* r0 = sqt + (16 * mt + l15) * 72 + 32 * ks + 4 * g;
;                 acc = mfma16(bs[ks], ld4x2(r0, r0 + 16), acc);
;             }
;             bf16_t* ob = OG + (size_t)prow(b, dir, 32 * c) * 512 + 128 * h;
;             u32x2 ov; ov.x = pk2(acc[0], acc[1]); ov.y = pk2(acc[2], acc[3]);
;             *(u32x2*)(ob + sgn * ((16 * mt + l15) * 512) + dv0 + 4 * g) = ov;
;         }
; #pragma unroll
;         for (int dt = 0; dt < 4; ++dt) {
;             const bf16x8 ak = tr2(sko + (8 * g + q4) * 72 + 16 * dt + 4 * p4, sko + (8 * g + 4 + q4) * 72 + 16 * dt + 4 * p4);
; #pragma unroll
;             for (int r = 0; r < 4; ++r) st[dt][r] *= sdc[16 * dt + 4 * g + r];
;             st[dt] = mfma16(ak, vb, st[dt]);
;         }
;     };
.LBB0_630:
	v_cvt_pk_bf16_f32 v94, v72, v73
	v_cvt_pk_bf16_f32 v93, v90, v91
	v_cvt_pk_bf16_f32 v92, v88, v89
	v_cvt_pk_bf16_f32 v95, v74, v75
	s_waitcnt lgkmcnt(9)
	v_mfma_f32_16x16x32_bf16 v[80:83], v[200:203], v[204:207], 0
	ds_read_b64_tr_b16 v[236:237], v143 offset:7168
	ds_read_b64_tr_b16 v[240:241], v143 offset:7200
	ds_read2_b32 v[244:245], v158 offset1:1
	s_add_i32 s4, s26, 64
	s_add_i32 s5, s26, 0xffffff40
	s_add_i32 s6, s27, 32
	s_add_i32 s7, s27, 0xfffff820
	s_and_b64 s[2:3], s[0:1], exec
	s_cselect_b32 s2, s4, s7
	s_waitcnt lgkmcnt(11)
	v_mfma_f32_16x16x32_bf16 v[80:83], v[92:95], v[208:211], v[80:83]
	ds_read2_b32 v[246:247], v157 offset1:1
	v_cvt_pk_bf16_f32 v190, v84, v85
	v_cvt_pk_bf16_f32 v189, v78, v79
	v_cvt_pk_bf16_f32 v188, v76, v77
	v_cvt_pk_bf16_f32 v191, v86, v87
	s_add_i32 s4, s2, s22
	s_and_b64 s[2:3], s[0:1], exec
	s_cselect_b32 s2, s5, s6
	s_add_i32 s2, s2, s21
	s_cmp_lt_u32 s24, 4
	s_waitcnt lgkmcnt(11)
	v_mfma_f32_16x16x32_bf16 v[80:83], v[188:191], v[212:215], v[80:83]
	ds_read_b64_tr_b16 v[248:249], v143 offset:7232
	s_cselect_b32 s2, s4, s2
	s_ashr_i32 s3, s2, 31
	s_lshl_b64 s[36:37], s[2:3], 10
	s_nop 3
	v_cvt_pk_bf16_f32 v80, v80, v81
	v_cvt_pk_bf16_f32 v81, v82, v83
	v_lshl_add_u64 v[82:83], v[100:101], 0, s[36:37]
	global_store_dwordx2 v[82:83], v[80:81], off
	s_waitcnt lgkmcnt(10)
	v_mfma_f32_16x16x32_bf16 v[80:83], v[200:203], v[224:227], 0
	ds_read_b64_tr_b16 v[250:251], v144 offset:7232
	ds_read2_b32 v[204:205], v154 offset1:1
	v_mfma_f32_16x16x32_bf16 v[80:83], v[92:95], v[216:219], v[80:83]
	s_waitcnt lgkmcnt(11)
	v_mfma_f32_16x16x32_bf16 v[80:83], v[188:191], v[228:231], v[80:83]
	ds_read2_b32 v[206:207], v155 offset1:1
	s_nop 7
	v_cvt_pk_bf16_f32 v80, v80, v81
	v_cvt_pk_bf16_f32 v81, v82, v83
	v_lshl_add_u64 v[82:83], v[102:103], 0, s[36:37]
	global_store_dwordx2 v[82:83], v[80:81], off
	s_waitcnt lgkmcnt(11)
	v_pk_mul_f32 v[80:81], v[88:89], v[232:233]
	ds_read_b64_tr_b16 v[208:209], v143 offset:7264
	s_waitcnt lgkmcnt(11)
	v_pk_mul_f32 v[82:83], v[90:91], v[234:235]
	ds_read_b64_tr_b16 v[210:211], v144 offset:7264
	s_waitcnt lgkmcnt(9)
	v_mfma_f32_16x16x32_bf16 v[92:95], v[236:239], v[200:203], v[80:83]
	ds_read2_b32 v[212:213], v161 offset1:1
	ds_read2_b32 v[214:215], v160 offset1:1
	s_nop 2
	s_waitcnt lgkmcnt(9)
	v_pk_mul_f32 v[72:73], v[72:73], v[244:245]
	s_waitcnt lgkmcnt(8)
	v_pk_mul_f32 v[74:75], v[74:75], v[246:247]
	s_nop 1
	v_mfma_f32_16x16x32_bf16 v[72:75], v[240:243], v[200:203], v[72:75]
	s_waitcnt lgkmcnt(5)
	v_pk_mul_f32 v[76:77], v[76:77], v[204:205]
	s_waitcnt lgkmcnt(4)
	v_pk_mul_f32 v[78:79], v[78:79], v[206:207]
	s_nop 1
	v_mfma_f32_16x16x32_bf16 v[80:83], v[248:251], v[200:203], v[76:79]
	s_nop 2
	s_waitcnt vmcnt(11)
	ds_write_b128 v121, v[60:63] offset:32512
	s_waitcnt vmcnt(10)
	ds_write_b128 v122, v[68:71] offset:20736
	s_waitcnt lgkmcnt(3)
	v_pk_mul_f32 v[84:85], v[84:85], v[212:213]
	s_waitcnt lgkmcnt(2)
	v_pk_mul_f32 v[86:87], v[86:87], v[214:215]
	s_nop 1
	v_mfma_f32_16x16x32_bf16 v[88:91], v[208:211], v[200:203], v[84:87]
	s_and_saveexec_b64 s[36:37], s[38:39]
	ds_write_b128 v148, v[64:67] offset:20736
	s_or_b64 exec, exec, s[36:37]
	s_and_saveexec_b64 s[36:37], s[40:41]
	ds_write_b32 v149, v120 offset:40704
	s_or_b64 exec, exec, s[36:37]
	s_cmp_gt_u32 s24, 60
	s_waitcnt lgkmcnt(0)
	s_barrier
	s_cbranch_scc1 .LBB0_579
	v_add_u32_e32 v60, 0x120, v150
	s_movk_i32 s2, 0x100
	v_cmp_gt_i32_e32 vcc, s2, v60
	v_add_u32_e32 v61, 32, v150
	v_mov_b32_e32 v63, s22
	v_cndmask_b32_e32 v62, v174, v175, vcc
	v_add3_u32 v62, v132, v62, s27
	v_cndmask_b32_e32 v60, v61, v60, vcc
	v_mov_b32_e32 v61, s21
	v_add_u32_e32 v62, 0xfffff641, v62
	v_cndmask_b32_e32 v61, v61, v63, vcc
	v_cndmask_b32_e64 v60, v62, v60, s[0:1]
	v_add_u32_e32 v60, v60, v61
	s_movk_i32 s2, 0x3800
	v_add_co_u32_e32 v68, vcc, 0xb000, v112
	v_mad_i64_i32 v[60:61], s[2:3], v60, s2, v[104:105]
	s_nop 0
	v_addc_co_u32_e32 v69, vcc, 0, v113, vcc
	global_load_dwordx4 v[60:63], v[60:61], off offset:1024
	s_nop 0
	global_load_dwordx4 v[68:71], v[68:69], off nt
	s_and_saveexec_b64 s[36:37], s[38:39]
	s_cbranch_execz .LBB0_637
	v_lshl_add_u64 v[64:65], v[106:107], 0, s[44:45]
	v_add_co_u32_e32 v64, vcc, 0x12841000, v64
	s_nop 1
	v_addc_co_u32_e32 v65, vcc, 0, v65, vcc
	global_load_dwordx4 v[64:67], v[64:65], off offset:2048 nt
